# grid barrier: L1 invalidate (buffer_inv sc1) issued at barrier entry instead of after the release is observed; the CU issues no L1-cached loads in between
# speedup vs baseline: 1.0049x; 1.0049x over previous
.Lbar_skip_wb:
	s_waitcnt lgkmcnt(0)
	s_waitcnt vmcnt(0)
	buffer_inv sc1
	v_mbcnt_lo_u32_b32 v0, s22, 0
	v_mbcnt_hi_u32_b32 v0, s23, v0
	v_cmp_eq_u32_e32 vcc, 0, v0
	s_and_saveexec_b64 s[26:27], vcc
	s_cbranch_execz .LBB0_56
	s_bcnt1_i32_b64 s5, s[22:23]
	v_readlane_b32 s8, v254, 29
	v_mov_b32_e32 v3, s5
	v_readlane_b32 s9, v254, 30
	s_nop 4
	global_atomic_add v3, v1, v3, s[8:9] sc0

.LBB0_70:
	s_or_b64 exec, exec, s[22:23]
	s_mov_b64 s[22:23], exec
	v_mbcnt_lo_u32_b32 v0, s22, 0
	v_mbcnt_hi_u32_b32 v0, s23, v0
	v_cmp_eq_u32_e32 vcc, 0, v0
	s_waitcnt vmcnt(0)
	s_and_saveexec_b64 s[26:27], vcc
	s_cbranch_execz .LBB0_72
	s_bcnt1_i32_b64 s5, s[22:23]
	v_readlane_b32 s8, v254, 27
	v_mov_b32_e32 v0, s5
	v_readlane_b32 s9, v254, 28
	s_nop 4
	global_atomic_add v1, v0, s[8:9]
